# resid epilogue stores without nt hint (on top of batched resid loads, NSA cmp wait move, setprio pair removal)
# speedup vs baseline: 1.0027x; 1.0019x over previous
;     __device__ __forceinline__ void operator()(const f32x4 (&acc)[2][2][4][2], const Unit& u, int wr, int wc, int fr, int fq) const { gated_store<1>(acc, u, wr, wc, fr, fq, G, ldg); }
;     __device__ __forceinline__ void operator()(const f32x4 (&acc)[2][2][4][2], const Unit& u, int wr, int wc, int fr, int fq) const {
;         const int col0 = u.pn * BM + wc * 32 + 4 * fq;
; #pragma unroll
;         for (int ai = 0; ai < 2; ++ai)
; #pragma unroll
;             for (int m = 0; m < 4; ++m) { const size_t off = (size_t)(u.pm * BM + ai * HALF + wr * 64 + m * 16 + fr) * ldc + col0;
; #pragma unroll
;                 for (int bj = 0; bj < 2; ++bj)
; #pragma unroll
;                     for (int n = 0; n < 2; ++n) { const f32x4 bs = *(const f32x4*)(base + off + bj * HALF + n * 16); __builtin_nontemporal_store(bs + acc[ai][bj][m][n], (f32x4*)(out + off + bj * HALF + n * 16)); } }
;     }
.LBB0_1141:
	v_lshl_add_u32 v142, s28, 8, v144
	v_lshl_or_b32 v140, s50, 8, v146
	v_ashrrev_i32_e32 v143, 31, v142
	v_ashrrev_i32_e32 v141, 31, v140
	v_lshlrev_b64 v[150:151], 11, v[142:143]
	v_lshl_add_u64 v[150:151], v[150:151], 0, v[140:141]
	v_lshlrev_b64 v[154:155], 2, v[150:151]
	v_lshl_add_u64 v[156:157], s[10:11], 0, v[154:155]
	v_lshl_add_u64 v[154:155], s[8:9], 0, v[154:155]
	s_andn2_b64 vcc, exec, s[6:7]
	s_mov_b64 s[6:7], -1
	s_mov_b64 s[98:99], 0x20000
	s_mov_b64 s[100:101], 0xa0000
	global_load_dwordx4 v[140:143], v[156:157], off
	global_load_dwordx4 v[150:153], v[156:157], off offset:64
	global_load_dwordx4 v[158:161], v[156:157], off offset:512
	global_load_dwordx4 v[162:165], v[156:157], off offset:576
	v_lshl_add_u64 v[156:157], v[156:157], 0, s[98:99]
	global_load_dwordx4 v[166:169], v[156:157], off
	global_load_dwordx4 v[170:173], v[156:157], off offset:64
	global_load_dwordx4 v[174:177], v[156:157], off offset:512
	global_load_dwordx4 v[178:181], v[156:157], off offset:576
	v_lshl_add_u64 v[156:157], v[156:157], 0, s[98:99]
	global_load_dwordx4 v[182:185], v[156:157], off
	global_load_dwordx4 v[186:189], v[156:157], off offset:64
	global_load_dwordx4 v[190:193], v[156:157], off offset:512
	global_load_dwordx4 v[198:201], v[156:157], off offset:576
	s_waitcnt vmcnt(11)
	v_pk_add_f32 v[126:127], v[126:127], v[142:143]
	v_pk_add_f32 v[124:125], v[124:125], v[140:141]
	global_store_dwordx4 v[154:155], v[124:127], off
	v_lshl_add_u64 v[156:157], v[156:157], 0, s[98:99]
	global_load_dwordx4 v[140:143], v[156:157], off
	s_waitcnt vmcnt(12)
	v_pk_add_f32 v[122:123], v[122:123], v[152:153]
	v_pk_add_f32 v[120:121], v[120:121], v[150:151]
	global_store_dwordx4 v[154:155], v[120:123], off offset:64
	global_load_dwordx4 v[150:153], v[156:157], off offset:64
	s_waitcnt vmcnt(13)
	v_pk_add_f32 v[118:119], v[118:119], v[160:161]
	v_pk_add_f32 v[116:117], v[116:117], v[158:159]
	global_store_dwordx4 v[154:155], v[116:119], off offset:512
	global_load_dwordx4 v[158:161], v[156:157], off offset:512
	s_waitcnt vmcnt(14)
	v_pk_add_f32 v[106:107], v[106:107], v[164:165]
	v_pk_add_f32 v[104:105], v[104:105], v[162:163]
	global_store_dwordx4 v[154:155], v[104:107], off offset:576
	global_load_dwordx4 v[162:165], v[156:157], off offset:576
	s_waitcnt vmcnt(15)
	v_pk_add_f32 v[114:115], v[114:115], v[168:169]
	v_pk_add_f32 v[112:113], v[112:113], v[166:167]
	v_lshl_add_u64 v[154:155], v[154:155], 0, s[98:99]
	global_store_dwordx4 v[154:155], v[112:115], off
	v_lshl_add_u64 v[156:157], v[156:157], 0, s[100:101]
	global_load_dwordx4 v[166:169], v[156:157], off
	s_waitcnt vmcnt(16)
	v_pk_add_f32 v[110:111], v[110:111], v[172:173]
	v_pk_add_f32 v[108:109], v[108:109], v[170:171]
	global_store_dwordx4 v[154:155], v[108:111], off offset:64
	global_load_dwordx4 v[170:173], v[156:157], off offset:64
	s_waitcnt vmcnt(17)
	v_pk_add_f32 v[102:103], v[102:103], v[176:177]
	v_pk_add_f32 v[100:101], v[100:101], v[174:175]
	global_store_dwordx4 v[154:155], v[100:103], off offset:512
	global_load_dwordx4 v[174:177], v[156:157], off offset:512
	s_waitcnt vmcnt(18)
	v_pk_add_f32 v[90:91], v[90:91], v[180:181]
	v_pk_add_f32 v[88:89], v[88:89], v[178:179]
	global_store_dwordx4 v[154:155], v[88:91], off offset:576
	global_load_dwordx4 v[178:181], v[156:157], off offset:576
	s_waitcnt vmcnt(19)
	v_pk_add_f32 v[98:99], v[98:99], v[184:185]
	v_pk_add_f32 v[96:97], v[96:97], v[182:183]
	v_lshl_add_u64 v[154:155], v[154:155], 0, s[98:99]
	global_store_dwordx4 v[154:155], v[96:99], off
	v_lshl_add_u64 v[156:157], v[156:157], 0, s[98:99]
	global_load_dwordx4 v[182:185], v[156:157], off
	s_waitcnt vmcnt(20)
	v_pk_add_f32 v[94:95], v[94:95], v[188:189]
	v_pk_add_f32 v[92:93], v[92:93], v[186:187]
	global_store_dwordx4 v[154:155], v[92:95], off offset:64
	global_load_dwordx4 v[186:189], v[156:157], off offset:64
	s_waitcnt vmcnt(21)
	v_pk_add_f32 v[86:87], v[86:87], v[192:193]
	v_pk_add_f32 v[84:85], v[84:85], v[190:191]
	global_store_dwordx4 v[154:155], v[84:87], off offset:512
	global_load_dwordx4 v[190:193], v[156:157], off offset:512
	s_waitcnt vmcnt(22)
	v_pk_add_f32 v[74:75], v[74:75], v[200:201]
	v_pk_add_f32 v[72:73], v[72:73], v[198:199]
	global_store_dwordx4 v[154:155], v[72:75], off offset:576
	global_load_dwordx4 v[198:201], v[156:157], off offset:576
	s_waitcnt vmcnt(22)
; #define PG8_WAIT_V(n) asm volatile("s_waitcnt vmcnt(" #n ")" ::: "memory")
; #define PG8_BAR __builtin_amdgcn_s_barrier()
;     __device__ __forceinline__ void operator()(const f32x4 (&acc)[2][2][4][2], const Unit& u, int wr, int wc, int fr, int fq) const {
;     ...
;             for (int m = 0; m < 4; ++m) { const size_t off = (size_t)(u.pm * BM + ai * HALF + wr * 64 + m * 16 + fr) * ldc + col0;
; #pragma unroll
;                 for (int bj = 0; bj < 2; ++bj)
; #pragma unroll
;                     for (int n = 0; n < 2; ++n) { const f32x4 bs = *(const f32x4*)(base + off + bj * HALF + n * 16); __builtin_nontemporal_store(bs + acc[ai][bj][m][n], (f32x4*)(out + off + bj * HALF + n * 16)); } }
;     }
; template <class Epi, class Sched, bool ALIGN_EPI = false, bool SP2 = false>
; __device__ __forceinline__ void gemm_phase(PG8_LAS unsigned char* lds, const Gemm g, const Sched& S, const Epi& E) {
;     ...
;         if constexpr (!Epi::AFTER_DRAIN) { E(acc, cur, wr, wc, fr, fq); S.done(cur); }
;         if (!has_next) break;
; #pragma unroll
;         for (int a = 0; a < 2; ++a)
; #pragma unroll
;             for (int b = 0; b < 2; ++b)
; #pragma unroll
;                 for (int m = 0; m < 4; ++m)
; #pragma unroll
;                     for (int n = 0; n < 2; ++n) acc[a][b][m][n] = (f32x4){0.f, 0.f, 0.f, 0.f};
;         cur = nxt; cA = nA; cB = nB; ++ui;
;         if constexpr (ALIGN_EPI) { if (wr == 1) PG8_BAR; }
;     }
;     PG8_WAIT_V(0);
;     if constexpr (!ALIGN_EPI) { if (wr == 0) PG8_BAR; }
;     PG8_BAR;
	v_pk_add_f32 v[82:83], v[82:83], v[142:143]
	v_pk_add_f32 v[80:81], v[80:81], v[140:141]
	v_lshl_add_u64 v[154:155], v[154:155], 0, s[98:99]
	global_store_dwordx4 v[154:155], v[80:83], off
	v_lshl_add_u64 v[156:157], v[156:157], 0, s[98:99]
	global_load_dwordx4 v[140:143], v[156:157], off
	s_waitcnt vmcnt(22)
	v_pk_add_f32 v[78:79], v[78:79], v[152:153]
	v_pk_add_f32 v[76:77], v[76:77], v[150:151]
	global_store_dwordx4 v[154:155], v[76:79], off offset:64
	global_load_dwordx4 v[150:153], v[156:157], off offset:64
	s_waitcnt vmcnt(22)
	v_pk_add_f32 v[70:71], v[70:71], v[160:161]
	v_pk_add_f32 v[68:69], v[68:69], v[158:159]
	global_store_dwordx4 v[154:155], v[68:71], off offset:512
	global_load_dwordx4 v[158:161], v[156:157], off offset:512
	s_waitcnt vmcnt(22)
	v_pk_add_f32 v[66:67], v[66:67], v[164:165]
	v_pk_add_f32 v[64:65], v[64:65], v[162:163]
	global_store_dwordx4 v[154:155], v[64:67], off offset:576
	global_load_dwordx4 v[162:165], v[156:157], off offset:576
	s_waitcnt vmcnt(22)
	v_pk_add_f32 v[62:63], v[62:63], v[168:169]
	v_pk_add_f32 v[60:61], v[60:61], v[166:167]
	v_lshl_add_u64 v[154:155], v[154:155], 0, s[100:101]
	global_store_dwordx4 v[154:155], v[60:63], off
	v_lshl_add_u64 v[156:157], v[156:157], 0, s[98:99]
	global_load_dwordx4 v[166:169], v[156:157], off
	s_waitcnt vmcnt(22)
	v_pk_add_f32 v[58:59], v[58:59], v[172:173]
	v_pk_add_f32 v[56:57], v[56:57], v[170:171]
	global_store_dwordx4 v[154:155], v[56:59], off offset:64
	global_load_dwordx4 v[170:173], v[156:157], off offset:64
	s_waitcnt vmcnt(22)
	v_pk_add_f32 v[54:55], v[54:55], v[176:177]
	v_pk_add_f32 v[52:53], v[52:53], v[174:175]
	global_store_dwordx4 v[154:155], v[52:55], off offset:512
	global_load_dwordx4 v[174:177], v[156:157], off offset:512
	s_waitcnt vmcnt(22)
	v_pk_add_f32 v[42:43], v[42:43], v[180:181]
	v_pk_add_f32 v[40:41], v[40:41], v[178:179]
	global_store_dwordx4 v[154:155], v[40:43], off offset:576
	global_load_dwordx4 v[178:181], v[156:157], off offset:576
	s_waitcnt vmcnt(22)
	v_pk_add_f32 v[50:51], v[50:51], v[184:185]
	v_pk_add_f32 v[48:49], v[48:49], v[182:183]
	v_lshl_add_u64 v[154:155], v[154:155], 0, s[98:99]
	global_store_dwordx4 v[154:155], v[48:51], off
	s_waitcnt vmcnt(21)
	v_pk_add_f32 v[46:47], v[46:47], v[188:189]
	v_pk_add_f32 v[44:45], v[44:45], v[186:187]
	global_store_dwordx4 v[154:155], v[44:47], off offset:64
	s_waitcnt vmcnt(20)
	v_pk_add_f32 v[38:39], v[38:39], v[192:193]
	v_pk_add_f32 v[36:37], v[36:37], v[190:191]
	global_store_dwordx4 v[154:155], v[36:39], off offset:512
	s_waitcnt vmcnt(19)
	v_pk_add_f32 v[26:27], v[26:27], v[200:201]
	v_pk_add_f32 v[24:25], v[24:25], v[198:199]
	global_store_dwordx4 v[154:155], v[24:27], off offset:576
	s_waitcnt vmcnt(18)
	v_pk_add_f32 v[34:35], v[34:35], v[142:143]
	v_pk_add_f32 v[32:33], v[32:33], v[140:141]
	v_lshl_add_u64 v[154:155], v[154:155], 0, s[98:99]
	global_store_dwordx4 v[154:155], v[32:35], off
	s_waitcnt vmcnt(17)
	v_pk_add_f32 v[30:31], v[30:31], v[152:153]
	v_pk_add_f32 v[28:29], v[28:29], v[150:151]
	global_store_dwordx4 v[154:155], v[28:31], off offset:64
	s_waitcnt vmcnt(16)
	v_pk_add_f32 v[22:23], v[22:23], v[160:161]
	v_pk_add_f32 v[20:21], v[20:21], v[158:159]
	global_store_dwordx4 v[154:155], v[20:23], off offset:512
	s_waitcnt vmcnt(15)
	v_pk_add_f32 v[10:11], v[10:11], v[164:165]
	v_pk_add_f32 v[8:9], v[8:9], v[162:163]
	global_store_dwordx4 v[154:155], v[8:11], off offset:576
	s_waitcnt vmcnt(14)
	v_pk_add_f32 v[18:19], v[18:19], v[168:169]
	v_pk_add_f32 v[16:17], v[16:17], v[166:167]
	v_lshl_add_u64 v[154:155], v[154:155], 0, s[98:99]
	global_store_dwordx4 v[154:155], v[16:19], off
	s_waitcnt vmcnt(13)
	v_pk_add_f32 v[14:15], v[14:15], v[172:173]
	v_pk_add_f32 v[12:13], v[12:13], v[170:171]
	global_store_dwordx4 v[154:155], v[12:15], off offset:64
	s_waitcnt vmcnt(12)
	v_pk_add_f32 v[6:7], v[6:7], v[176:177]
	v_pk_add_f32 v[4:5], v[4:5], v[174:175]
	global_store_dwordx4 v[154:155], v[4:7], off offset:512
	s_waitcnt vmcnt(11)
	v_pk_add_f32 v[2:3], v[2:3], v[180:181]
	v_pk_add_f32 v[0:1], v[0:1], v[178:179]
	global_store_dwordx4 v[154:155], v[0:3], off offset:576
	s_cbranch_vccnz .LBB0_1130
	s_andn2_b64 vcc, exec, s[14:15]
	s_cbranch_vccnz .LBB0_1129
	s_barrier
	s_branch .LBB0_1129

;     __device__ __forceinline__ void operator()(const f32x4 (&acc)[2][2][4][2], const Unit& u, int wr, int wc, int fr, int fq) const { gated_store<1>(acc, u, wr, wc, fr, fq, G, ldg); }
;     __device__ __forceinline__ void operator()(const f32x4 (&acc)[2][2][4][2], const Unit& u, int wr, int wc, int fr, int fq) const {
;         const int col0 = u.pn * BM + wc * 32 + 4 * fq;
; #pragma unroll
;         for (int ai = 0; ai < 2; ++ai)
; #pragma unroll
;             for (int m = 0; m < 4; ++m) { const size_t off = (size_t)(u.pm * BM + ai * HALF + wr * 64 + m * 16 + fr) * ldc + col0;
; #pragma unroll
;                 for (int bj = 0; bj < 2; ++bj)
; #pragma unroll
;                     for (int n = 0; n < 2; ++n) { const f32x4 bs = *(const f32x4*)(base + off + bj * HALF + n * 16); __builtin_nontemporal_store(bs + acc[ai][bj][m][n], (f32x4*)(out + off + bj * HALF + n * 16)); } }
;     }
.LBB0_1353:
	v_lshl_add_u32 v142, s45, 8, v144
	v_lshl_or_b32 v140, s46, 8, v146
	v_ashrrev_i32_e32 v143, 31, v142
	v_ashrrev_i32_e32 v141, 31, v140
	v_lshlrev_b64 v[150:151], 13, v[142:143]
	v_lshl_add_u64 v[150:151], s[12:13], 0, v[150:151]
	v_lshlrev_b64 v[140:141], 2, v[140:141]
	v_lshl_add_u64 v[154:155], v[150:151], 0, v[140:141]
	s_mov_b64 s[22:23], -1
	s_and_b64 vcc, exec, s[6:7]
	s_mov_b64 s[98:99], 0x20000
	s_mov_b64 s[100:101], 0xa0000
	v_mov_b64_e32 v[210:211], v[154:155]
	global_load_dwordx4 v[140:143], v[210:211], off
	global_load_dwordx4 v[150:153], v[210:211], off offset:64
	global_load_dwordx4 v[158:161], v[210:211], off offset:512
	global_load_dwordx4 v[162:165], v[210:211], off offset:576
	v_lshl_add_u64 v[210:211], v[210:211], 0, s[98:99]
	global_load_dwordx4 v[166:169], v[210:211], off
	global_load_dwordx4 v[170:173], v[210:211], off offset:64
	global_load_dwordx4 v[174:177], v[210:211], off offset:512
	global_load_dwordx4 v[178:181], v[210:211], off offset:576
	v_lshl_add_u64 v[210:211], v[210:211], 0, s[98:99]
	global_load_dwordx4 v[182:185], v[210:211], off
	global_load_dwordx4 v[186:189], v[210:211], off offset:64
	global_load_dwordx4 v[190:193], v[210:211], off offset:512
	global_load_dwordx4 v[198:201], v[210:211], off offset:576
	s_waitcnt vmcnt(11)
	v_pk_add_f32 v[126:127], v[126:127], v[142:143]
	v_pk_add_f32 v[124:125], v[124:125], v[140:141]
	global_store_dwordx4 v[154:155], v[124:127], off
	v_lshl_add_u64 v[210:211], v[210:211], 0, s[98:99]
	global_load_dwordx4 v[140:143], v[210:211], off
	s_waitcnt vmcnt(12)
	v_pk_add_f32 v[122:123], v[122:123], v[152:153]
	v_pk_add_f32 v[120:121], v[120:121], v[150:151]
	global_store_dwordx4 v[154:155], v[120:123], off offset:64
	global_load_dwordx4 v[150:153], v[210:211], off offset:64
	s_waitcnt vmcnt(13)
	v_pk_add_f32 v[118:119], v[118:119], v[160:161]
	v_pk_add_f32 v[116:117], v[116:117], v[158:159]
	global_store_dwordx4 v[154:155], v[116:119], off offset:512
	global_load_dwordx4 v[158:161], v[210:211], off offset:512
	s_waitcnt vmcnt(14)
	v_pk_add_f32 v[110:111], v[110:111], v[164:165]
	v_pk_add_f32 v[108:109], v[108:109], v[162:163]
	global_store_dwordx4 v[154:155], v[108:111], off offset:576
	global_load_dwordx4 v[162:165], v[210:211], off offset:576
	s_waitcnt vmcnt(15)
	v_pk_add_f32 v[114:115], v[114:115], v[168:169]
	v_pk_add_f32 v[112:113], v[112:113], v[166:167]
	v_lshl_add_u64 v[154:155], v[154:155], 0, s[98:99]
	global_store_dwordx4 v[154:155], v[112:115], off
	v_lshl_add_u64 v[210:211], v[210:211], 0, s[100:101]
	global_load_dwordx4 v[166:169], v[210:211], off
	s_waitcnt vmcnt(16)
	v_pk_add_f32 v[106:107], v[106:107], v[172:173]
	v_pk_add_f32 v[104:105], v[104:105], v[170:171]
	global_store_dwordx4 v[154:155], v[104:107], off offset:64
	global_load_dwordx4 v[170:173], v[210:211], off offset:64
	s_waitcnt vmcnt(17)
	v_pk_add_f32 v[102:103], v[102:103], v[176:177]
	v_pk_add_f32 v[100:101], v[100:101], v[174:175]
	global_store_dwordx4 v[154:155], v[100:103], off offset:512
	global_load_dwordx4 v[174:177], v[210:211], off offset:512
	s_waitcnt vmcnt(18)
	v_pk_add_f32 v[98:99], v[98:99], v[180:181]
	v_pk_add_f32 v[96:97], v[96:97], v[178:179]
	global_store_dwordx4 v[154:155], v[96:99], off offset:576
	global_load_dwordx4 v[178:181], v[210:211], off offset:576
	s_waitcnt vmcnt(19)
	v_pk_add_f32 v[94:95], v[94:95], v[184:185]
	v_pk_add_f32 v[92:93], v[92:93], v[182:183]
	v_lshl_add_u64 v[154:155], v[154:155], 0, s[98:99]
	global_store_dwordx4 v[154:155], v[92:95], off
	v_lshl_add_u64 v[210:211], v[210:211], 0, s[98:99]
	global_load_dwordx4 v[182:185], v[210:211], off
	s_waitcnt vmcnt(20)
	v_pk_add_f32 v[90:91], v[90:91], v[188:189]
	v_pk_add_f32 v[88:89], v[88:89], v[186:187]
	global_store_dwordx4 v[154:155], v[88:91], off offset:64
	global_load_dwordx4 v[186:189], v[210:211], off offset:64
	s_waitcnt vmcnt(21)
	v_pk_add_f32 v[86:87], v[86:87], v[192:193]
	v_pk_add_f32 v[84:85], v[84:85], v[190:191]
	global_store_dwordx4 v[154:155], v[84:87], off offset:512
	global_load_dwordx4 v[190:193], v[210:211], off offset:512
	s_waitcnt vmcnt(22)
	v_pk_add_f32 v[82:83], v[82:83], v[200:201]
	v_pk_add_f32 v[80:81], v[80:81], v[198:199]
	global_store_dwordx4 v[154:155], v[80:83], off offset:576
	global_load_dwordx4 v[198:201], v[210:211], off offset:576
	s_waitcnt vmcnt(22)
;     __device__ __forceinline__ void operator()(const f32x4 (&acc)[2][2][4][2], const Unit& u, int wr, int wc, int fr, int fq) const { gated_store<1>(acc, u, wr, wc, fr, fq, G, ldg); }
; #define PG8_BAR __builtin_amdgcn_s_barrier()
;     __device__ __forceinline__ void operator()(const f32x4 (&acc)[2][2][4][2], const Unit& u, int wr, int wc, int fr, int fq) const {
;         const int col0 = u.pn * BM + wc * 32 + 4 * fq;
; #pragma unroll
;         for (int ai = 0; ai < 2; ++ai)
; #pragma unroll
;             for (int m = 0; m < 4; ++m) { const size_t off = (size_t)(u.pm * BM + ai * HALF + wr * 64 + m * 16 + fr) * ldc + col0;
; #pragma unroll
;                 for (int bj = 0; bj < 2; ++bj)
; #pragma unroll
;                     for (int n = 0; n < 2; ++n) { const f32x4 bs = *(const f32x4*)(base + off + bj * HALF + n * 16); __builtin_nontemporal_store(bs + acc[ai][bj][m][n], (f32x4*)(out + off + bj * HALF + n * 16)); } }
;     }
; template <class Epi, class Sched, bool ALIGN_EPI = false, bool SP2 = false>
; __device__ __forceinline__ void gemm_phase(PG8_LAS unsigned char* lds, const Gemm g, const Sched& S, const Epi& E) {
;     ...
;         if constexpr (ALIGN_EPI) { if (wr == 0) PG8_BAR; }
;         if constexpr (!Epi::AFTER_DRAIN) { E(acc, cur, wr, wc, fr, fq); S.done(cur); }
;         if (!has_next) break;
; #pragma unroll
;         for (int a = 0; a < 2; ++a)
; #pragma unroll
;             for (int b = 0; b < 2; ++b)
; #pragma unroll
;                 for (int m = 0; m < 4; ++m)
; #pragma unroll
;                     for (int n = 0; n < 2; ++n) acc[a][b][m][n] = (f32x4){0.f, 0.f, 0.f, 0.f};
;         cur = nxt; cA = nA; cB = nB; ++ui;
;         if constexpr (ALIGN_EPI) { if (wr == 1) PG8_BAR; }
	v_pk_add_f32 v[78:79], v[78:79], v[142:143]
	v_pk_add_f32 v[76:77], v[76:77], v[140:141]
	v_lshl_add_u64 v[154:155], v[154:155], 0, s[98:99]
	global_store_dwordx4 v[154:155], v[76:79], off
	v_lshl_add_u64 v[210:211], v[210:211], 0, s[98:99]
	global_load_dwordx4 v[140:143], v[210:211], off
	s_waitcnt vmcnt(22)
	v_pk_add_f32 v[74:75], v[74:75], v[152:153]
	v_pk_add_f32 v[72:73], v[72:73], v[150:151]
	global_store_dwordx4 v[154:155], v[72:75], off offset:64
	global_load_dwordx4 v[150:153], v[210:211], off offset:64
	s_waitcnt vmcnt(22)
	v_pk_add_f32 v[70:71], v[70:71], v[160:161]
	v_pk_add_f32 v[68:69], v[68:69], v[158:159]
	global_store_dwordx4 v[154:155], v[68:71], off offset:512
	global_load_dwordx4 v[158:161], v[210:211], off offset:512
	s_waitcnt vmcnt(22)
	v_pk_add_f32 v[66:67], v[66:67], v[164:165]
	v_pk_add_f32 v[64:65], v[64:65], v[162:163]
	global_store_dwordx4 v[154:155], v[64:67], off offset:576
	global_load_dwordx4 v[162:165], v[210:211], off offset:576
	s_waitcnt vmcnt(22)
	v_pk_add_f32 v[62:63], v[62:63], v[168:169]
	v_pk_add_f32 v[60:61], v[60:61], v[166:167]
	v_lshl_add_u64 v[154:155], v[154:155], 0, s[100:101]
	global_store_dwordx4 v[154:155], v[60:63], off
	v_lshl_add_u64 v[210:211], v[210:211], 0, s[98:99]
	global_load_dwordx4 v[166:169], v[210:211], off
	s_waitcnt vmcnt(22)
	v_pk_add_f32 v[58:59], v[58:59], v[172:173]
	v_pk_add_f32 v[56:57], v[56:57], v[170:171]
	global_store_dwordx4 v[154:155], v[56:59], off offset:64
	global_load_dwordx4 v[170:173], v[210:211], off offset:64
	s_waitcnt vmcnt(22)
	v_pk_add_f32 v[54:55], v[54:55], v[176:177]
	v_pk_add_f32 v[52:53], v[52:53], v[174:175]
	global_store_dwordx4 v[154:155], v[52:55], off offset:512
	global_load_dwordx4 v[174:177], v[210:211], off offset:512
	s_waitcnt vmcnt(22)
	v_pk_add_f32 v[50:51], v[50:51], v[180:181]
	v_pk_add_f32 v[48:49], v[48:49], v[178:179]
	global_store_dwordx4 v[154:155], v[48:51], off offset:576
	global_load_dwordx4 v[178:181], v[210:211], off offset:576
	s_waitcnt vmcnt(22)
	v_pk_add_f32 v[46:47], v[46:47], v[184:185]
	v_pk_add_f32 v[44:45], v[44:45], v[182:183]
	v_lshl_add_u64 v[154:155], v[154:155], 0, s[98:99]
	global_store_dwordx4 v[154:155], v[44:47], off
	s_waitcnt vmcnt(21)
	v_pk_add_f32 v[42:43], v[42:43], v[188:189]
	v_pk_add_f32 v[40:41], v[40:41], v[186:187]
	global_store_dwordx4 v[154:155], v[40:43], off offset:64
	s_waitcnt vmcnt(20)
	v_pk_add_f32 v[38:39], v[38:39], v[192:193]
	v_pk_add_f32 v[36:37], v[36:37], v[190:191]
	global_store_dwordx4 v[154:155], v[36:39], off offset:512
	s_waitcnt vmcnt(19)
	v_pk_add_f32 v[34:35], v[34:35], v[200:201]
	v_pk_add_f32 v[32:33], v[32:33], v[198:199]
	global_store_dwordx4 v[154:155], v[32:35], off offset:576
	s_waitcnt vmcnt(18)
	v_pk_add_f32 v[30:31], v[30:31], v[142:143]
	v_pk_add_f32 v[28:29], v[28:29], v[140:141]
	v_lshl_add_u64 v[154:155], v[154:155], 0, s[98:99]
	global_store_dwordx4 v[154:155], v[28:31], off
	s_waitcnt vmcnt(17)
	v_pk_add_f32 v[26:27], v[26:27], v[152:153]
	v_pk_add_f32 v[24:25], v[24:25], v[150:151]
	global_store_dwordx4 v[154:155], v[24:27], off offset:64
	s_waitcnt vmcnt(16)
	v_pk_add_f32 v[22:23], v[22:23], v[160:161]
	v_pk_add_f32 v[20:21], v[20:21], v[158:159]
	global_store_dwordx4 v[154:155], v[20:23], off offset:512
	s_waitcnt vmcnt(15)
	v_pk_add_f32 v[18:19], v[18:19], v[164:165]
	v_pk_add_f32 v[16:17], v[16:17], v[162:163]
	global_store_dwordx4 v[154:155], v[16:19], off offset:576
	s_waitcnt vmcnt(14)
	v_pk_add_f32 v[14:15], v[14:15], v[168:169]
	v_pk_add_f32 v[12:13], v[12:13], v[166:167]
	v_lshl_add_u64 v[154:155], v[154:155], 0, s[98:99]
	global_store_dwordx4 v[154:155], v[12:15], off
	s_waitcnt vmcnt(13)
	v_pk_add_f32 v[10:11], v[10:11], v[172:173]
	v_pk_add_f32 v[8:9], v[8:9], v[170:171]
	global_store_dwordx4 v[154:155], v[8:11], off offset:64
	s_waitcnt vmcnt(12)
	v_pk_add_f32 v[6:7], v[6:7], v[176:177]
	v_pk_add_f32 v[4:5], v[4:5], v[174:175]
	global_store_dwordx4 v[154:155], v[4:7], off offset:512
	s_waitcnt vmcnt(11)
	v_pk_add_f32 v[2:3], v[2:3], v[180:181]
	v_pk_add_f32 v[0:1], v[0:1], v[178:179]
	global_store_dwordx4 v[154:155], v[0:3], off offset:576
	s_cbranch_vccnz .LBB0_1338
	s_andn2_b64 vcc, exec, s[14:15]
	s_cbranch_vccnz .LBB0_1337
	s_barrier
	s_branch .LBB0_1337

;     __device__ __forceinline__ void operator()(const f32x4 (&acc)[2][2][4][2], const Unit& u, int wr, int wc, int fr, int fq) const { gated_store<1>(acc, u, wr, wc, fr, fq, G, ldg); }
;     __device__ __forceinline__ void operator()(const f32x4 (&acc)[2][2][4][2], const Unit& u, int wr, int wc, int fr, int fq) const {
;         const int col0 = u.pn * BM + wc * 32 + 4 * fq;
; #pragma unroll
;         for (int ai = 0; ai < 2; ++ai)
; #pragma unroll
;             for (int m = 0; m < 4; ++m) { const size_t off = (size_t)(u.pm * BM + ai * HALF + wr * 64 + m * 16 + fr) * ldc + col0;
; #pragma unroll
;                 for (int bj = 0; bj < 2; ++bj)
; #pragma unroll
;                     for (int n = 0; n < 2; ++n) { const f32x4 bs = *(const f32x4*)(base + off + bj * HALF + n * 16); __builtin_nontemporal_store(bs + acc[ai][bj][m][n], (f32x4*)(out + off + bj * HALF + n * 16)); } }
;     }
.LBB0_2036:
	v_lshl_add_u32 v142, s26, 8, v144
	v_lshl_or_b32 v140, s27, 8, v146
	v_ashrrev_i32_e32 v143, 31, v142
	v_ashrrev_i32_e32 v141, 31, v140
	v_lshlrev_b64 v[150:151], 13, v[142:143]
	v_lshl_add_u64 v[150:151], s[8:9], 0, v[150:151]
	v_lshlrev_b64 v[140:141], 2, v[140:141]
	v_lshl_add_u64 v[154:155], v[150:151], 0, v[140:141]
	s_mov_b64 s[26:27], -1
	s_andn2_b64 vcc, exec, s[6:7]
	s_mov_b64 s[98:99], 0x20000
	s_mov_b64 s[100:101], 0xa0000
	v_mov_b64_e32 v[210:211], v[154:155]
	global_load_dwordx4 v[140:143], v[210:211], off
	global_load_dwordx4 v[150:153], v[210:211], off offset:64
	global_load_dwordx4 v[158:161], v[210:211], off offset:512
	global_load_dwordx4 v[162:165], v[210:211], off offset:576
	v_lshl_add_u64 v[210:211], v[210:211], 0, s[98:99]
	global_load_dwordx4 v[166:169], v[210:211], off
	global_load_dwordx4 v[170:173], v[210:211], off offset:64
	global_load_dwordx4 v[174:177], v[210:211], off offset:512
	global_load_dwordx4 v[178:181], v[210:211], off offset:576
	v_lshl_add_u64 v[210:211], v[210:211], 0, s[98:99]
	global_load_dwordx4 v[182:185], v[210:211], off
	global_load_dwordx4 v[186:189], v[210:211], off offset:64
	global_load_dwordx4 v[190:193], v[210:211], off offset:512
	global_load_dwordx4 v[198:201], v[210:211], off offset:576
	s_waitcnt vmcnt(11)
	v_pk_add_f32 v[126:127], v[126:127], v[142:143]
	v_pk_add_f32 v[124:125], v[124:125], v[140:141]
	global_store_dwordx4 v[154:155], v[124:127], off
	v_lshl_add_u64 v[210:211], v[210:211], 0, s[98:99]
	global_load_dwordx4 v[140:143], v[210:211], off
	s_waitcnt vmcnt(12)
	v_pk_add_f32 v[122:123], v[122:123], v[152:153]
	v_pk_add_f32 v[120:121], v[120:121], v[150:151]
	global_store_dwordx4 v[154:155], v[120:123], off offset:64
	global_load_dwordx4 v[150:153], v[210:211], off offset:64
	s_waitcnt vmcnt(13)
	v_pk_add_f32 v[118:119], v[118:119], v[160:161]
	v_pk_add_f32 v[116:117], v[116:117], v[158:159]
	global_store_dwordx4 v[154:155], v[116:119], off offset:512
	global_load_dwordx4 v[158:161], v[210:211], off offset:512
	s_waitcnt vmcnt(14)
	v_pk_add_f32 v[110:111], v[110:111], v[164:165]
	v_pk_add_f32 v[108:109], v[108:109], v[162:163]
	global_store_dwordx4 v[154:155], v[108:111], off offset:576
	global_load_dwordx4 v[162:165], v[210:211], off offset:576
	s_waitcnt vmcnt(15)
	v_pk_add_f32 v[114:115], v[114:115], v[168:169]
	v_pk_add_f32 v[112:113], v[112:113], v[166:167]
	v_lshl_add_u64 v[154:155], v[154:155], 0, s[98:99]
	global_store_dwordx4 v[154:155], v[112:115], off
	v_lshl_add_u64 v[210:211], v[210:211], 0, s[100:101]
	global_load_dwordx4 v[166:169], v[210:211], off
	s_waitcnt vmcnt(16)
	v_pk_add_f32 v[106:107], v[106:107], v[172:173]
	v_pk_add_f32 v[104:105], v[104:105], v[170:171]
	global_store_dwordx4 v[154:155], v[104:107], off offset:64
	global_load_dwordx4 v[170:173], v[210:211], off offset:64
	s_waitcnt vmcnt(17)
	v_pk_add_f32 v[102:103], v[102:103], v[176:177]
	v_pk_add_f32 v[100:101], v[100:101], v[174:175]
	global_store_dwordx4 v[154:155], v[100:103], off offset:512
	global_load_dwordx4 v[174:177], v[210:211], off offset:512
	s_waitcnt vmcnt(18)
	v_pk_add_f32 v[98:99], v[98:99], v[180:181]
	v_pk_add_f32 v[96:97], v[96:97], v[178:179]
	global_store_dwordx4 v[154:155], v[96:99], off offset:576
	global_load_dwordx4 v[178:181], v[210:211], off offset:576
	s_waitcnt vmcnt(19)
	v_pk_add_f32 v[94:95], v[94:95], v[184:185]
	v_pk_add_f32 v[92:93], v[92:93], v[182:183]
	v_lshl_add_u64 v[154:155], v[154:155], 0, s[98:99]
	global_store_dwordx4 v[154:155], v[92:95], off
	v_lshl_add_u64 v[210:211], v[210:211], 0, s[98:99]
	global_load_dwordx4 v[182:185], v[210:211], off
	s_waitcnt vmcnt(20)
	v_pk_add_f32 v[90:91], v[90:91], v[188:189]
	v_pk_add_f32 v[88:89], v[88:89], v[186:187]
	global_store_dwordx4 v[154:155], v[88:91], off offset:64
	global_load_dwordx4 v[186:189], v[210:211], off offset:64
	s_waitcnt vmcnt(21)
	v_pk_add_f32 v[86:87], v[86:87], v[192:193]
	v_pk_add_f32 v[84:85], v[84:85], v[190:191]
	global_store_dwordx4 v[154:155], v[84:87], off offset:512
	global_load_dwordx4 v[190:193], v[210:211], off offset:512
	s_waitcnt vmcnt(22)
	v_pk_add_f32 v[82:83], v[82:83], v[200:201]
	v_pk_add_f32 v[80:81], v[80:81], v[198:199]
	global_store_dwordx4 v[154:155], v[80:83], off offset:576
	global_load_dwordx4 v[198:201], v[210:211], off offset:576
	s_waitcnt vmcnt(22)
;     __device__ __forceinline__ void operator()(const f32x4 (&acc)[2][2][4][2], const Unit& u, int wr, int wc, int fr, int fq) const { gated_store<1>(acc, u, wr, wc, fr, fq, G, ldg); }
; #define PG8_BAR __builtin_amdgcn_s_barrier()
;     __device__ __forceinline__ void operator()(const f32x4 (&acc)[2][2][4][2], const Unit& u, int wr, int wc, int fr, int fq) const {
;         const int col0 = u.pn * BM + wc * 32 + 4 * fq;
; #pragma unroll
;         for (int ai = 0; ai < 2; ++ai)
; #pragma unroll
;             for (int m = 0; m < 4; ++m) { const size_t off = (size_t)(u.pm * BM + ai * HALF + wr * 64 + m * 16 + fr) * ldc + col0;
; #pragma unroll
;                 for (int bj = 0; bj < 2; ++bj)
; #pragma unroll
;                     for (int n = 0; n < 2; ++n) { const f32x4 bs = *(const f32x4*)(base + off + bj * HALF + n * 16); __builtin_nontemporal_store(bs + acc[ai][bj][m][n], (f32x4*)(out + off + bj * HALF + n * 16)); } }
;     }
; template <class Epi, class Sched, bool ALIGN_EPI = false, bool SP2 = false>
; __device__ __forceinline__ void gemm_phase(PG8_LAS unsigned char* lds, const Gemm g, const Sched& S, const Epi& E) {
;     ...
;         if constexpr (ALIGN_EPI) { if (wr == 0) PG8_BAR; }
;         if constexpr (!Epi::AFTER_DRAIN) { E(acc, cur, wr, wc, fr, fq); S.done(cur); }
;         if (!has_next) break;
; #pragma unroll
;         for (int a = 0; a < 2; ++a)
; #pragma unroll
;             for (int b = 0; b < 2; ++b)
; #pragma unroll
;                 for (int m = 0; m < 4; ++m)
; #pragma unroll
;                     for (int n = 0; n < 2; ++n) acc[a][b][m][n] = (f32x4){0.f, 0.f, 0.f, 0.f};
;         cur = nxt; cA = nA; cB = nB; ++ui;
;         if constexpr (ALIGN_EPI) { if (wr == 1) PG8_BAR; }
	v_pk_add_f32 v[78:79], v[78:79], v[142:143]
	v_pk_add_f32 v[76:77], v[76:77], v[140:141]
	v_lshl_add_u64 v[154:155], v[154:155], 0, s[98:99]
	global_store_dwordx4 v[154:155], v[76:79], off
	v_lshl_add_u64 v[210:211], v[210:211], 0, s[98:99]
	global_load_dwordx4 v[140:143], v[210:211], off
	s_waitcnt vmcnt(22)
	v_pk_add_f32 v[74:75], v[74:75], v[152:153]
	v_pk_add_f32 v[72:73], v[72:73], v[150:151]
	global_store_dwordx4 v[154:155], v[72:75], off offset:64
	global_load_dwordx4 v[150:153], v[210:211], off offset:64
	s_waitcnt vmcnt(22)
	v_pk_add_f32 v[70:71], v[70:71], v[160:161]
	v_pk_add_f32 v[68:69], v[68:69], v[158:159]
	global_store_dwordx4 v[154:155], v[68:71], off offset:512
	global_load_dwordx4 v[158:161], v[210:211], off offset:512
	s_waitcnt vmcnt(22)
	v_pk_add_f32 v[66:67], v[66:67], v[164:165]
	v_pk_add_f32 v[64:65], v[64:65], v[162:163]
	global_store_dwordx4 v[154:155], v[64:67], off offset:576
	global_load_dwordx4 v[162:165], v[210:211], off offset:576
	s_waitcnt vmcnt(22)
	v_pk_add_f32 v[62:63], v[62:63], v[168:169]
	v_pk_add_f32 v[60:61], v[60:61], v[166:167]
	v_lshl_add_u64 v[154:155], v[154:155], 0, s[100:101]
	global_store_dwordx4 v[154:155], v[60:63], off
	v_lshl_add_u64 v[210:211], v[210:211], 0, s[98:99]
	global_load_dwordx4 v[166:169], v[210:211], off
	s_waitcnt vmcnt(22)
	v_pk_add_f32 v[58:59], v[58:59], v[172:173]
	v_pk_add_f32 v[56:57], v[56:57], v[170:171]
	global_store_dwordx4 v[154:155], v[56:59], off offset:64
	global_load_dwordx4 v[170:173], v[210:211], off offset:64
	s_waitcnt vmcnt(22)
	v_pk_add_f32 v[54:55], v[54:55], v[176:177]
	v_pk_add_f32 v[52:53], v[52:53], v[174:175]
	global_store_dwordx4 v[154:155], v[52:55], off offset:512
	global_load_dwordx4 v[174:177], v[210:211], off offset:512
	s_waitcnt vmcnt(22)
	v_pk_add_f32 v[50:51], v[50:51], v[180:181]
	v_pk_add_f32 v[48:49], v[48:49], v[178:179]
	global_store_dwordx4 v[154:155], v[48:51], off offset:576
	global_load_dwordx4 v[178:181], v[210:211], off offset:576
	s_waitcnt vmcnt(22)
	v_pk_add_f32 v[46:47], v[46:47], v[184:185]
	v_pk_add_f32 v[44:45], v[44:45], v[182:183]
	v_lshl_add_u64 v[154:155], v[154:155], 0, s[98:99]
	global_store_dwordx4 v[154:155], v[44:47], off
	s_waitcnt vmcnt(21)
	v_pk_add_f32 v[42:43], v[42:43], v[188:189]
	v_pk_add_f32 v[40:41], v[40:41], v[186:187]
	global_store_dwordx4 v[154:155], v[40:43], off offset:64
	s_waitcnt vmcnt(20)
	v_pk_add_f32 v[38:39], v[38:39], v[192:193]
	v_pk_add_f32 v[36:37], v[36:37], v[190:191]
	global_store_dwordx4 v[154:155], v[36:39], off offset:512
	s_waitcnt vmcnt(19)
	v_pk_add_f32 v[34:35], v[34:35], v[200:201]
	v_pk_add_f32 v[32:33], v[32:33], v[198:199]
	global_store_dwordx4 v[154:155], v[32:35], off offset:576
	s_waitcnt vmcnt(18)
	v_pk_add_f32 v[30:31], v[30:31], v[142:143]
	v_pk_add_f32 v[28:29], v[28:29], v[140:141]
	v_lshl_add_u64 v[154:155], v[154:155], 0, s[98:99]
	global_store_dwordx4 v[154:155], v[28:31], off
	s_waitcnt vmcnt(17)
	v_pk_add_f32 v[26:27], v[26:27], v[152:153]
	v_pk_add_f32 v[24:25], v[24:25], v[150:151]
	global_store_dwordx4 v[154:155], v[24:27], off offset:64
	s_waitcnt vmcnt(16)
	v_pk_add_f32 v[22:23], v[22:23], v[160:161]
	v_pk_add_f32 v[20:21], v[20:21], v[158:159]
	global_store_dwordx4 v[154:155], v[20:23], off offset:512
	s_waitcnt vmcnt(15)
	v_pk_add_f32 v[18:19], v[18:19], v[164:165]
	v_pk_add_f32 v[16:17], v[16:17], v[162:163]
	global_store_dwordx4 v[154:155], v[16:19], off offset:576
	s_waitcnt vmcnt(14)
	v_pk_add_f32 v[14:15], v[14:15], v[168:169]
	v_pk_add_f32 v[12:13], v[12:13], v[166:167]
	v_lshl_add_u64 v[154:155], v[154:155], 0, s[98:99]
	global_store_dwordx4 v[154:155], v[12:15], off
	s_waitcnt vmcnt(13)
	v_pk_add_f32 v[10:11], v[10:11], v[172:173]
	v_pk_add_f32 v[8:9], v[8:9], v[170:171]
	global_store_dwordx4 v[154:155], v[8:11], off offset:64
	s_waitcnt vmcnt(12)
	v_pk_add_f32 v[6:7], v[6:7], v[176:177]
	v_pk_add_f32 v[4:5], v[4:5], v[174:175]
	global_store_dwordx4 v[154:155], v[4:7], off offset:512
	s_waitcnt vmcnt(11)
	v_pk_add_f32 v[2:3], v[2:3], v[180:181]
	v_pk_add_f32 v[0:1], v[0:1], v[178:179]
	global_store_dwordx4 v[154:155], v[0:3], off offset:576
	s_cbranch_vccnz .LBB0_2025
	s_andn2_b64 vcc, exec, s[10:11]
	s_cbranch_vccnz .LBB0_2024
	s_barrier
	s_branch .LBB0_2024
